# chunk unit SSD conv loop: per-step global loads software-pipelined one iteration ahead (4 loads in flight instead of load+wait per step)
# speedup vs baseline: 1.0954x; 1.0224x over previous
; DEV uint32_t pk2(float lo, float hi) { f32x2 v; v[0] = lo; v[1] = hi; bf16v2 b = __builtin_convertvector(v, bf16v2); return __builtin_bit_cast(uint32_t, b); }
; DEV float bflo(uint32_t u) { return __uint_as_float(u << 16); }
; DEV float bfhi(uint32_t u) { return __uint_as_float(u & 0xffff0000u); }
; DEV void chunk_unit(CParams& p, int layer, int mode, int b, int c, char* lds, const int swave) {
;     ...
;   auto ld_pair = [&](int t, int col, const float* st, int stw) -> uint32_t {
;     if (t >= L) return 0u;
;     if (t >= 0) return *(const uint32_t*)(proj + (size_t)(row0 + t) * PW + col);
;     if (mode == 2) { const float* s = st + (size_t)(3 + t) * stw; return pk2(s[0], s[1]); }
;     if (c > 0) return *(const uint32_t*)(proj + (size_t)(row0 + t) * PW + col);
;     return 0u;
;     ...
;     for (int item = tid; item < npairs * 4; item += 256) {
;       const int pr = item % npairs, tq = item / npairs, ch = pr * 2;
;       const float w00 = cw[ch], w01 = cw[ch + 1], w10 = cw[768 + ch], w11 = cw[768 + ch + 1], w20 = cw[1536 + ch], w21 = cw[1536 + ch + 1], w30 = cw[2304 + ch], w31 = cw[2304 + ch + 1];
;       const float b0 = cb[ch], b1 = cb[ch + 1];
;       const float* st = p.in[6] + ((size_t)(layer * 8 + b) * 3) * 768 + ch;
;       const int sec = ch >> 8, cl = ch & 255, hd = cl >> 6;
;       float x0a, x0b, x1a, x1b, x2a, x2b;
;       {
;         uint32_t u;
;         u = ld_pair(tq * 16 - 3, C_XBC + ch, st, 768); x0a = bflo(u); x0b = bfhi(u);
;         u = ld_pair(tq * 16 - 2, C_XBC + ch, st, 768); x1a = bflo(u); x1b = bfhi(u);
;         u = ld_pair(tq * 16 - 1, C_XBC + ch, st, 768); x2a = bflo(u); x2b = bfhi(u);
;       }
;       const float cslast = csL[63 * 4 + hd];
; #pragma unroll 4
;       for (int tt = 0; tt < 16; ++tt) {
;         const int t = tq * 16 + tt;
;         const uint32_t u = ld_pair(t, C_XBC + ch, st, 768);
.LBB0_809:
	s_or_b64 exec, exec, s[90:91]
	v_bfe_u32 v29, v10, 6, 2
	v_and_b32_e32 v27, 0xfe, v10
	s_add_i32 s6, 16, 0x24400
	v_lshlrev_b32_e32 v10, 2, v29
	v_cmp_gt_u32_e32 vcc, s55, v21
	s_waitcnt lgkmcnt(4)
	v_add_u32_e32 v24, s6, v10
	s_and_b64 s[90:91], s[78:79], vcc
	v_cmp_lt_i32_e32 vcc, -1, v20
	v_lshl_or_b32 v10, v19, 8, v10
	v_lshlrev_b32_e32 v20, 8, v18
	s_waitcnt vmcnt(0)
	v_lshlrev_b32_e32 v12, 16, v11
	v_and_b32_e32 v13, 0xffff0000, v11
	v_lshrrev_b32_e32 v11, 7, v21
	v_sub_u32_e32 v25, v10, v20
	v_lshlrev_b32_e32 v20, 4, v19
	v_lshlrev_b32_e32 v21, 4, v18
	v_sub_u32_e32 v10, v20, v21
	v_or_b32_e32 v26, 3, v10
	v_mul_lo_u32 v10, v19, s10
	v_lshl_or_b32 v10, v27, 1, v10
	v_mul_i32_i24_e32 v28, 0x2400, v18
	ds_read_b32 v24, v24 offset:1008
	v_sub_u32_e32 v27, v10, v28
	v_mad_u64_u32 v[10:11], s[6:7], v11, s13, v[10:11]
	v_sub_u32_e32 v28, v10, v28
	v_add_u32_e32 v10, s43, v20
	v_sub_u32_e32 v20, v10, v21
	v_lshlrev_b64 v[10:11], 1, v[240:241]
	v_lshl_or_b32 v19, v19, 6, v29
	v_lshlrev_b32_e32 v18, 6, v18
	v_mad_i64_i32 v[10:11], s[6:7], v20, s16, v[10:11]
	v_sub_u32_e32 v18, v19, v18
	v_lshlrev_b32_e32 v14, 16, v15
	v_and_b32_e32 v15, 0xffff0000, v15
	v_lshlrev_b32_e32 v16, 16, v17
	v_and_b32_e32 v17, 0xffff0000, v17
	s_or_b64 s[92:93], vcc, s[86:87]
	v_lshl_add_u64 v[10:11], s[62:63], 0, v[10:11]
	v_lshlrev_b32_e32 v29, 2, v18
	s_mov_b64 s[94:95], 0
	v_lshl_add_u64 v[186:187], v[10:11], 0, s[94:95]
	v_add_u32_e32 v188, -3, v26
	v_cmp_gt_i32_e64 s[100:101], 64, v188
	s_and_b64 vcc, s[100:101], s[92:93]
	s_and_saveexec_b64 s[100:101], vcc
	v_add_co_u32_e32 v190, vcc, 0xc484000, v186
	s_nop 1
	v_addc_co_u32_e32 v191, vcc, 0, v187, vcc
	global_load_dword v192, v[190:191], off
	s_or_b64 exec, exec, s[100:101]
	v_add_u32_e32 v188, -2, v26
	v_cmp_gt_i32_e64 s[100:101], 64, v188
	s_and_b64 vcc, s[100:101], s[92:93]
	s_and_saveexec_b64 s[100:101], vcc
	v_add_co_u32_e32 v190, vcc, 0xc485000, v186
	s_nop 1
	v_addc_co_u32_e32 v191, vcc, 0, v187, vcc
	global_load_dword v193, v[190:191], off offset:2048
	s_or_b64 exec, exec, s[100:101]
	v_add_u32_e32 v188, -1, v26
	v_cmp_gt_i32_e64 s[100:101], 64, v188
	s_and_b64 vcc, s[100:101], s[92:93]
	s_and_saveexec_b64 s[100:101], vcc
	v_add_co_u32_e32 v190, vcc, 0xc487000, v186
	s_nop 1
	v_addc_co_u32_e32 v191, vcc, 0, v187, vcc
	global_load_dword v194, v[190:191], off
	s_or_b64 exec, exec, s[100:101]
	v_add_u32_e32 v188, 0, v26
	v_cmp_gt_i32_e64 s[100:101], 64, v188
	s_and_b64 vcc, s[100:101], s[92:93]
	s_and_saveexec_b64 s[100:101], vcc
	v_add_co_u32_e32 v190, vcc, 0xc488000, v186
	s_nop 1
	v_addc_co_u32_e32 v191, vcc, 0, v187, vcc
	global_load_dword v195, v[190:191], off offset:2048
	s_or_b64 exec, exec, s[100:101]
	s_branch .LBB0_811

; DEV uint32_t pk2(float lo, float hi) { f32x2 v; v[0] = lo; v[1] = hi; bf16v2 b = __builtin_convertvector(v, bf16v2); return __builtin_bit_cast(uint32_t, b); }
; DEV float bflo(uint32_t u) { return __uint_as_float(u << 16); }
; DEV float bfhi(uint32_t u) { return __uint_as_float(u & 0xffff0000u); }
; DEV float fexp(float x) { return __builtin_amdgcn_exp2f(x * 1.4426950408889634f); }
; DEV float siluf_(float x) { return x * frcp(1.f + fexp(-x)); }
; DEV void chunk_unit(CParams& p, int layer, int mode, int b, int c, char* lds, const int swave) {
;     ...
;   auto ld_pair = [&](int t, int col, const float* st, int stw) -> uint32_t {
;     if (t >= L) return 0u;
;     if (t >= 0) return *(const uint32_t*)(proj + (size_t)(row0 + t) * PW + col);
;     if (mode == 2) { const float* s = st + (size_t)(3 + t) * stw; return pk2(s[0], s[1]); }
;     if (c > 0) return *(const uint32_t*)(proj + (size_t)(row0 + t) * PW + col);
;     return 0u;
;     ...
; #pragma unroll 4
;       for (int tt = 0; tt < 16; ++tt) {
;         const int t = tq * 16 + tt;
;         const uint32_t u = ld_pair(t, C_XBC + ch, st, 768);
;         const float xa = bflo(u), xb = bfhi(u);
;         float oa = siluf_(b0 + w00 * x0a + w10 * x1a + w20 * x2a + w30 * xa);
;         float ob = siluf_(b1 + w01 * x0b + w11 * x1b + w21 * x2b + w31 * xb);
;         if (t >= L) { oa = 0.f; ob = 0.f; }
;         *(uint32_t*)(lds + sec * SLOT + t * CS_B + cl * 2) = pk2(oa, ob);
;         if (sec == 0 && mode != 1) {
;           const float sc = fexp(cslast - csL[t * 4 + hd]) * dtL[t * 4 + hd];
;           *(uint32_t*)(lds + 3 * SLOT + t * CS_B + cl * 2) = pk2(oa * sc, ob * sc);
;         }
.LBB0_811:
	s_waitcnt vmcnt(0)
	v_mov_b32_e32 v196, v192
	v_mov_b32_e32 v197, v193
	v_mov_b32_e32 v198, v194
	v_mov_b32_e32 v199, v195
	v_lshl_add_u64 v[186:187], v[10:11], 0, s[94:95]
	v_add_u32_e32 v188, 1, v26
	v_cmp_gt_i32_e64 s[100:101], 64, v188
	s_and_b64 vcc, s[100:101], s[92:93]
	s_and_saveexec_b64 s[100:101], vcc
	v_add_co_u32_e32 v190, vcc, 0xc48a000, v186
	s_nop 1
	v_addc_co_u32_e32 v191, vcc, 0, v187, vcc
	global_load_dword v192, v[190:191], off
	s_or_b64 exec, exec, s[100:101]
	v_add_u32_e32 v188, 2, v26
	v_cmp_gt_i32_e64 s[100:101], 64, v188
	s_and_b64 vcc, s[100:101], s[92:93]
	s_and_saveexec_b64 s[100:101], vcc
	v_add_co_u32_e32 v190, vcc, 0xc48b000, v186
	s_nop 1
	v_addc_co_u32_e32 v191, vcc, 0, v187, vcc
	global_load_dword v193, v[190:191], off offset:2048
	s_or_b64 exec, exec, s[100:101]
	v_add_u32_e32 v188, 3, v26
	v_cmp_gt_i32_e64 s[100:101], 64, v188
	s_and_b64 vcc, s[100:101], s[92:93]
	s_and_saveexec_b64 s[100:101], vcc
	v_add_co_u32_e32 v190, vcc, 0xc48d000, v186
	s_nop 1
	v_addc_co_u32_e32 v191, vcc, 0, v187, vcc
	global_load_dword v194, v[190:191], off
	s_or_b64 exec, exec, s[100:101]
	v_add_u32_e32 v188, 4, v26
	v_cmp_gt_i32_e64 s[100:101], 64, v188
	s_and_b64 vcc, s[100:101], s[92:93]
	s_and_saveexec_b64 s[100:101], vcc
	v_add_co_u32_e32 v190, vcc, 0xc48e000, v186
	s_nop 1
	v_addc_co_u32_e32 v191, vcc, 0, v187, vcc
	global_load_dword v195, v[190:191], off offset:2048
	s_or_b64 exec, exec, s[100:101]
	v_add_u32_e32 v18, -3, v26
	v_cmp_gt_i32_e64 s[6:7], 64, v18
	s_and_b64 vcc, s[6:7], s[92:93]
	v_mov_b32_e32 v21, 0
	v_lshl_add_u64 v[18:19], v[10:11], 0, s[94:95]
	s_and_saveexec_b64 s[96:97], vcc
	s_cbranch_execz .LBB0_813
	v_mov_b32_e32 v21, v196
.LBB0_813:
	s_or_b64 exec, exec, s[96:97]
	v_pk_fma_f32 v[14:15], v[2:3], v[14:15], v[8:9]
	v_lshlrev_b32_e32 v20, 16, v21
	v_pk_fma_f32 v[14:15], v[0:1], v[12:13], v[14:15]
	v_and_b32_e32 v21, 0xffff0000, v21
	v_pk_fma_f32 v[14:15], v[4:5], v[16:17], v[14:15]
	s_nop 0
	v_pk_fma_f32 v[14:15], v[6:7], v[20:21], v[14:15]
	s_nop 0
	v_mul_f32_e32 v30, 0xbfb8aa3b, v14
	v_mul_f32_e32 v31, 0xbfb8aa3b, v15
	v_exp_f32_e32 v30, v30
	v_exp_f32_e32 v31, v31
	v_add_f32_e32 v30, 1.0, v30
	v_add_f32_e32 v31, 1.0, v31
	v_rcp_f32_e32 v30, v30
	v_rcp_f32_e32 v31, v31
	s_nop 0
	v_pk_mul_f32 v[14:15], v[14:15], v[30:31]
	s_nop 0
	v_cndmask_b32_e64 v15, 0, v15, s[6:7]
	v_cndmask_b32_e64 v14, 0, v14, s[6:7]
	v_cvt_pk_bf16_f32 v30, v14, v15
	v_add_u32_e32 v31, 16, v28
	ds_write_b32 v31, v30
	v_add_u32_e32 v30, 16, v27
	s_and_saveexec_b64 s[6:7], s[90:91]
	s_cbranch_execz .LBB0_815
	v_add_u32_e32 v32, 16, v29
	v_add_u32_e32 v33, 0x24400, v32
	ds_read_b32 v33, v33
	v_add_u32_e32 v32, 0x24000, v32
	ds_read_b32 v32, v32
	s_waitcnt lgkmcnt(1)
	v_sub_f32_e32 v33, v24, v33
	v_mul_f32_e32 v33, 0x3fb8aa3b, v33
	v_exp_f32_e32 v33, v33
	s_waitcnt lgkmcnt(0)
	v_mul_f32_e32 v32, v32, v33
	v_pk_mul_f32 v[14:15], v[14:15], v[32:33] op_sel_hi:[1,0]
	s_nop 0
	v_cvt_pk_bf16_f32 v14, v14, v15
	v_add_u32_e32 v15, 0x1b000, v30
	ds_write_b32 v15, v14
.LBB0_815:
	s_or_b64 exec, exec, s[6:7]
	v_add_u32_e32 v14, -2, v26
	v_cmp_gt_i32_e64 s[6:7], 64, v14
	s_and_b64 vcc, s[6:7], s[92:93]
	v_mov_b32_e32 v15, 0
	s_and_saveexec_b64 s[96:97], vcc
	s_cbranch_execz .LBB0_817
	v_mov_b32_e32 v15, v197
; DEV uint32_t pk2(float lo, float hi) { f32x2 v; v[0] = lo; v[1] = hi; bf16v2 b = __builtin_convertvector(v, bf16v2); return __builtin_bit_cast(uint32_t, b); }
; DEV float bflo(uint32_t u) { return __uint_as_float(u << 16); }
; DEV float bfhi(uint32_t u) { return __uint_as_float(u & 0xffff0000u); }
; DEV float fexp(float x) { return __builtin_amdgcn_exp2f(x * 1.4426950408889634f); }
; DEV float siluf_(float x) { return x * frcp(1.f + fexp(-x)); }
; DEV void chunk_unit(CParams& p, int layer, int mode, int b, int c, char* lds, const int swave) {
;     ...
; #pragma unroll 4
;       for (int tt = 0; tt < 16; ++tt) {
;         const int t = tq * 16 + tt;
;         const uint32_t u = ld_pair(t, C_XBC + ch, st, 768);
;         const float xa = bflo(u), xb = bfhi(u);
;         float oa = siluf_(b0 + w00 * x0a + w10 * x1a + w20 * x2a + w30 * xa);
;         float ob = siluf_(b1 + w01 * x0b + w11 * x1b + w21 * x2b + w31 * xb);
;         if (t >= L) { oa = 0.f; ob = 0.f; }
;         *(uint32_t*)(lds + sec * SLOT + t * CS_B + cl * 2) = pk2(oa, ob);
;         if (sec == 0 && mode != 1) {
;           const float sc = fexp(cslast - csL[t * 4 + hd]) * dtL[t * 4 + hd];
;           *(uint32_t*)(lds + 3 * SLOT + t * CS_B + cl * 2) = pk2(oa * sc, ob * sc);
;         }
;         x0a = x1a; x0b = x1b; x1a = x2a; x1b = x2b; x2a = xa; x2b = xb;
;       }
.LBB0_817:
	s_or_b64 exec, exec, s[96:97]
	v_pk_fma_f32 v[12:13], v[2:3], v[12:13], v[8:9]
	v_lshlrev_b32_e32 v14, 16, v15
	v_pk_fma_f32 v[12:13], v[0:1], v[16:17], v[12:13]
	v_and_b32_e32 v15, 0xffff0000, v15
	v_pk_fma_f32 v[12:13], v[4:5], v[20:21], v[12:13]
	s_nop 0
	v_pk_fma_f32 v[12:13], v[6:7], v[14:15], v[12:13]
	s_nop 0
	v_mul_f32_e32 v32, 0xbfb8aa3b, v12
	v_mul_f32_e32 v33, 0xbfb8aa3b, v13
	v_exp_f32_e32 v32, v32
	v_exp_f32_e32 v33, v33
	v_add_f32_e32 v32, 1.0, v32
	v_add_f32_e32 v33, 1.0, v33
	v_rcp_f32_e32 v32, v32
	v_rcp_f32_e32 v33, v33
	s_nop 0
	v_pk_mul_f32 v[12:13], v[12:13], v[32:33]
	s_nop 0
	v_cndmask_b32_e64 v13, 0, v13, s[6:7]
	v_cndmask_b32_e64 v12, 0, v12, s[6:7]
	v_cvt_pk_bf16_f32 v32, v12, v13
	ds_write_b32 v31, v32 offset:576
	v_add_u32_e32 v32, 16, v25
	s_and_saveexec_b64 s[6:7], s[90:91]
	s_cbranch_execz .LBB0_819
	v_add_u32_e32 v33, 0x24410, v32
	ds_read_b32 v33, v33
	v_add_u32_e32 v34, 0x24010, v32
	ds_read_b32 v34, v34
	s_waitcnt lgkmcnt(1)
	v_sub_f32_e32 v33, v24, v33
	v_mul_f32_e32 v33, 0x3fb8aa3b, v33
	v_exp_f32_e32 v33, v33
	s_waitcnt lgkmcnt(0)
	v_mul_f32_e32 v34, v34, v33
	v_pk_mul_f32 v[12:13], v[12:13], v[34:35] op_sel_hi:[1,0]
	s_nop 0
	v_cvt_pk_bf16_f32 v12, v12, v13
	v_add_u32_e32 v13, 0x1b240, v30
	ds_write_b32 v13, v12
.LBB0_819:
	s_or_b64 exec, exec, s[6:7]
	v_add_u32_e32 v12, -1, v26
	v_cmp_gt_i32_e64 s[6:7], 64, v12
	s_and_b64 vcc, s[6:7], s[92:93]
	v_mov_b32_e32 v13, 0
	s_and_saveexec_b64 s[96:97], vcc
	s_cbranch_execz .LBB0_821
	v_mov_b32_e32 v13, v198
.LBB0_821:
	s_or_b64 exec, exec, s[96:97]
	v_pk_fma_f32 v[16:17], v[2:3], v[16:17], v[8:9]
	v_lshlrev_b32_e32 v12, 16, v13
	v_pk_fma_f32 v[16:17], v[0:1], v[20:21], v[16:17]
	v_and_b32_e32 v13, 0xffff0000, v13
	v_pk_fma_f32 v[16:17], v[4:5], v[14:15], v[16:17]
	s_nop 0
	v_pk_fma_f32 v[16:17], v[6:7], v[12:13], v[16:17]
	s_nop 0
	v_mul_f32_e32 v33, 0xbfb8aa3b, v16
	v_exp_f32_e32 v33, v33
	v_mul_f32_e32 v34, 0xbfb8aa3b, v17
	v_exp_f32_e32 v35, v34
	v_add_f32_e32 v33, 1.0, v33
	v_rcp_f32_e32 v34, v33
	v_add_f32_e32 v33, 1.0, v35
	v_rcp_f32_e32 v35, v33
	s_nop 0
	v_pk_mul_f32 v[16:17], v[16:17], v[34:35]
	s_nop 0
	v_cndmask_b32_e64 v17, 0, v17, s[6:7]
	v_cndmask_b32_e64 v16, 0, v16, s[6:7]
	v_cvt_pk_bf16_f32 v33, v16, v17
	ds_write_b32 v31, v33 offset:1152
	s_and_saveexec_b64 s[6:7], s[90:91]
	s_cbranch_execz .LBB0_823
	v_add_u32_e32 v33, 0x24420, v32
	ds_read_b32 v33, v33
	v_add_u32_e32 v34, 0x24020, v32
	ds_read_b32 v34, v34
	s_waitcnt lgkmcnt(1)
	v_sub_f32_e32 v33, v24, v33
	v_mul_f32_e32 v33, 0x3fb8aa3b, v33
	v_exp_f32_e32 v33, v33
	s_waitcnt lgkmcnt(0)
	v_mul_f32_e32 v34, v34, v33
	v_pk_mul_f32 v[16:17], v[16:17], v[34:35] op_sel_hi:[1,0]
	s_nop 0
	v_cvt_pk_bf16_f32 v16, v16, v17
	v_add_u32_e32 v17, 0x1b480, v30
	ds_write_b32 v17, v16
.LBB0_823:
	s_or_b64 exec, exec, s[6:7]
	v_cmp_gt_i32_e64 s[6:7], 64, v26
	s_and_b64 vcc, s[6:7], s[92:93]
	v_mov_b32_e32 v17, 0
	s_and_saveexec_b64 s[96:97], vcc
	s_cbranch_execz .LBB0_825
	v_mov_b32_e32 v17, v199
.LBB0_825:
	s_or_b64 exec, exec, s[96:97]
	v_pk_fma_f32 v[18:19], v[2:3], v[20:21], v[8:9]
	v_lshlrev_b32_e32 v16, 16, v17
	v_pk_fma_f32 v[18:19], v[0:1], v[14:15], v[18:19]
	v_and_b32_e32 v17, 0xffff0000, v17
	v_pk_fma_f32 v[18:19], v[4:5], v[12:13], v[18:19]
	s_nop 0
	v_pk_fma_f32 v[18:19], v[6:7], v[16:17], v[18:19]
	s_nop 0
	v_mul_f32_e32 v20, 0xbfb8aa3b, v18
	v_mul_f32_e32 v21, 0xbfb8aa3b, v19
	v_exp_f32_e32 v20, v20
	v_exp_f32_e32 v21, v21
	v_add_f32_e32 v20, 1.0, v20
	v_add_f32_e32 v21, 1.0, v21
	v_rcp_f32_e32 v20, v20
	v_rcp_f32_e32 v21, v21
	s_nop 0
	v_pk_mul_f32 v[18:19], v[18:19], v[20:21]
	s_nop 0
	v_cndmask_b32_e64 v19, 0, v19, s[6:7]
	v_cndmask_b32_e64 v18, 0, v18, s[6:7]
	v_cvt_pk_bf16_f32 v20, v18, v19
	ds_write_b32 v31, v20 offset:1728
	s_and_saveexec_b64 s[6:7], s[90:91]
	s_cbranch_execz .LBB0_810
	v_add_u32_e32 v20, 0x24430, v32
	ds_read_b32 v20, v20
	v_add_u32_e32 v21, 0x24030, v32
	ds_read_b32 v21, v21
	s_waitcnt lgkmcnt(1)
	v_sub_f32_e32 v20, v24, v20
	v_mul_f32_e32 v20, 0x3fb8aa3b, v20
	v_exp_f32_e32 v20, v20
	s_waitcnt lgkmcnt(0)
	v_mul_f32_e32 v20, v21, v20
	v_pk_mul_f32 v[18:19], v[18:19], v[20:21] op_sel_hi:[1,0]
	s_nop 0
	v_cvt_pk_bf16_f32 v18, v18, v19
	v_add_u32_e32 v19, 0x1b6c0, v30
	ds_write_b32 v19, v18
	s_branch .LBB0_810
